# grid barrier: non-leader workgroups issue the agent-scope L1 invalidate before polling the release word instead of after (on top of v5)
# speedup vs baseline: 1.0065x; 1.0065x over previous
.LBB0_95:
	s_or_b64 exec, exec, s[14:15]
	s_waitcnt lgkmcnt(1)
	v_cvt_f32_u32_e32 v4, v2
	s_waitcnt vmcnt(0)
	v_readfirstlane_b32 s1, v3
	v_sub_u32_e32 v3, 0, v2
	v_rcp_iflag_f32_e32 v4, v4
	v_add_u32_e32 v5, s1, v1
	v_mul_f32_e32 v4, 0x4f7ffffe, v4
	v_cvt_u32_f32_e32 v4, v4
	v_mul_lo_u32 v1, v3, v4
	v_mul_hi_u32 v1, v4, v1
	v_add_u32_e32 v1, v4, v1
	v_mul_hi_u32 v1, v5, v1
	v_mul_lo_u32 v3, v1, v2
	v_sub_u32_e32 v3, v5, v3
	v_add_u32_e32 v4, 1, v1
	v_cmp_ge_u32_e32 vcc, v3, v2
	s_nop 1
	v_cndmask_b32_e32 v1, v1, v4, vcc
	v_sub_u32_e32 v4, v3, v2
	v_cndmask_b32_e32 v3, v3, v4, vcc
	v_add_u32_e32 v4, 1, v1
	v_cmp_ge_u32_e32 vcc, v3, v2
	v_add_u32_e32 v3, 1, v5
	s_nop 0
	v_cndmask_b32_e32 v1, v1, v4, vcc
	v_mul_lo_u32 v4, v2, v1
	v_add_u32_e32 v2, v4, v2
	v_cmp_ne_u32_e32 vcc, v3, v2
	s_and_saveexec_b64 s[2:3], vcc
	s_xor_b64 s[8:9], exec, s[2:3]
	s_cbranch_execz .LBB0_109
	s_add_i32 s2, s0, 0x900
	s_mov_b32 s3, 0
	s_lshl_b64 s[2:3], s[2:3], 2
	s_add_u32 s16, s92, s2
	s_addc_u32 s17, s93, s3
	s_waitcnt lgkmcnt(0)
	v_mov_b32_e32 v0, 0
	buffer_inv sc1
	global_load_dword v2, v0, s[16:17] sc1
	s_waitcnt vmcnt(0)
	v_cmp_eq_u32_e32 vcc, v2, v1
	s_and_saveexec_b64 s[12:13], vcc
	s_cbranch_execz .LBB0_108
	s_add_u32 s14, s10, 0x1ce00200
	s_addc_u32 s15, s11, 0
	s_mov_b32 s1, 1
	s_mov_b64 s[18:19], 0
	s_branch .LBB0_99

.LBB0_108:
	s_or_b64 exec, exec, s[12:13]
	s_waitcnt vmcnt(0)
	s_waitcnt vmcnt(0)

.LBB0_381:
	s_or_b64 exec, exec, s[10:11]
	s_waitcnt lgkmcnt(1)
	v_cvt_f32_u32_e32 v5, v3
	s_waitcnt vmcnt(0)
	v_readfirstlane_b32 s8, v4
	v_sub_u32_e32 v4, 0, v3
	v_rcp_iflag_f32_e32 v5, v5
	v_add_u32_e32 v6, s8, v1
	v_mul_f32_e32 v5, 0x4f7ffffe, v5
	v_cvt_u32_f32_e32 v5, v5
	v_mul_lo_u32 v1, v4, v5
	v_mul_hi_u32 v1, v5, v1
	v_add_u32_e32 v1, v5, v1
	v_mul_hi_u32 v1, v6, v1
	v_mul_lo_u32 v4, v1, v3
	v_sub_u32_e32 v4, v6, v4
	v_add_u32_e32 v5, 1, v1
	v_sub_u32_e32 v7, v4, v3
	v_cmp_ge_u32_e32 vcc, v4, v3
	s_nop 1
	v_cndmask_b32_e32 v1, v1, v5, vcc
	v_cndmask_b32_e32 v4, v4, v7, vcc
	v_add_u32_e32 v5, 1, v1
	v_cmp_ge_u32_e32 vcc, v4, v3
	v_add_u32_e32 v4, 1, v6
	s_nop 0
	v_cndmask_b32_e32 v1, v1, v5, vcc
	v_mul_lo_u32 v5, v3, v1
	v_add_u32_e32 v3, v5, v3
	v_cmp_ne_u32_e32 vcc, v4, v3
	s_and_saveexec_b64 s[8:9], vcc
	s_xor_b64 s[8:9], exec, s[8:9]
	s_cbranch_execz .LBB0_395
	s_add_i32 s94, s24, 0x900
	s_lshl_b64 s[10:11], s[94:95], 2
	s_add_u32 s12, s92, s10
	s_addc_u32 s13, s93, s11
	s_waitcnt lgkmcnt(0)
	buffer_inv sc1
	global_load_dword v0, v2, s[12:13] sc1
	s_waitcnt vmcnt(0)
	v_cmp_eq_u32_e32 vcc, v0, v1
	s_and_saveexec_b64 s[10:11], vcc
	s_cbranch_execz .LBB0_394
	s_mov_b32 s25, 1
	s_mov_b64 s[14:15], 0
	s_branch .LBB0_385

.LBB0_394:
	s_or_b64 exec, exec, s[10:11]
	s_waitcnt vmcnt(0)
	s_waitcnt vmcnt(0)
	v_readlane_b32 s87, v254, 62
	v_readlane_b32 s94, v253, 3

.LBB0_436:
	s_or_b64 exec, exec, s[10:11]
	s_waitcnt lgkmcnt(1)
	v_cvt_f32_u32_e32 v5, v3
	s_waitcnt vmcnt(0)
	v_readfirstlane_b32 s8, v4
	v_sub_u32_e32 v4, 0, v3
	v_rcp_iflag_f32_e32 v5, v5
	v_add_u32_e32 v6, s8, v1
	v_mul_f32_e32 v5, 0x4f7ffffe, v5
	v_cvt_u32_f32_e32 v5, v5
	v_mul_lo_u32 v1, v4, v5
	v_mul_hi_u32 v1, v5, v1
	v_add_u32_e32 v1, v5, v1
	v_mul_hi_u32 v1, v6, v1
	v_mul_lo_u32 v4, v1, v3
	v_sub_u32_e32 v4, v6, v4
	v_add_u32_e32 v5, 1, v1
	v_cmp_ge_u32_e32 vcc, v4, v3
	s_nop 1
	v_cndmask_b32_e32 v1, v1, v5, vcc
	v_sub_u32_e32 v5, v4, v3
	v_cndmask_b32_e32 v4, v4, v5, vcc
	v_add_u32_e32 v5, 1, v1
	v_cmp_ge_u32_e32 vcc, v4, v3
	v_add_u32_e32 v4, 1, v6
	s_nop 0
	v_cndmask_b32_e32 v1, v1, v5, vcc
	v_mul_lo_u32 v5, v3, v1
	v_add_u32_e32 v3, v5, v3
	v_cmp_ne_u32_e32 vcc, v4, v3
	s_and_saveexec_b64 s[8:9], vcc
	s_xor_b64 s[8:9], exec, s[8:9]
	s_cbranch_execz .LBB0_450
	s_add_i32 s94, s24, 0x900
	s_lshl_b64 s[10:11], s[94:95], 2
	s_add_u32 s12, s92, s10
	s_addc_u32 s13, s93, s11
	s_waitcnt lgkmcnt(0)
	buffer_inv sc1
	global_load_dword v0, v2, s[12:13] sc1
	s_waitcnt vmcnt(0)
	v_cmp_eq_u32_e32 vcc, v0, v1
	s_and_saveexec_b64 s[10:11], vcc
	s_cbranch_execz .LBB0_449
	s_mov_b32 s25, 1
	s_mov_b64 s[14:15], 0
	s_branch .LBB0_440

.LBB0_631:
	s_or_b64 exec, exec, s[12:13]
	s_waitcnt lgkmcnt(1)
	v_cvt_f32_u32_e32 v5, v3
	s_waitcnt vmcnt(0)
	v_readfirstlane_b32 s7, v4
	v_sub_u32_e32 v4, 0, v3
	v_rcp_iflag_f32_e32 v5, v5
	v_add_u32_e32 v6, s7, v1
	v_mul_f32_e32 v5, 0x4f7ffffe, v5
	v_cvt_u32_f32_e32 v5, v5
	v_mul_lo_u32 v1, v4, v5
	v_mul_hi_u32 v1, v5, v1
	v_add_u32_e32 v1, v5, v1
	v_mul_hi_u32 v1, v6, v1
	v_mul_lo_u32 v4, v1, v3
	v_sub_u32_e32 v4, v6, v4
	v_add_u32_e32 v5, 1, v1
	v_cmp_ge_u32_e32 vcc, v4, v3
	s_nop 1
	v_cndmask_b32_e32 v1, v1, v5, vcc
	v_sub_u32_e32 v5, v4, v3
	v_cndmask_b32_e32 v4, v4, v5, vcc
	v_add_u32_e32 v5, 1, v1
	v_cmp_ge_u32_e32 vcc, v4, v3
	v_add_u32_e32 v4, 1, v6
	s_nop 0
	v_cndmask_b32_e32 v1, v1, v5, vcc
	v_mul_lo_u32 v5, v3, v1
	v_add_u32_e32 v3, v5, v3
	v_cmp_ne_u32_e32 vcc, v4, v3
	s_and_saveexec_b64 s[10:11], vcc
	s_xor_b64 s[10:11], exec, s[10:11]
	s_cbranch_execz .LBB0_645
	s_add_i32 s94, s6, 0x900
	s_lshl_b64 s[12:13], s[94:95], 2
	s_add_u32 s14, s92, s12
	s_addc_u32 s15, s93, s13
	s_waitcnt lgkmcnt(0)
	buffer_inv sc1
	global_load_dword v0, v2, s[14:15] sc1
	s_waitcnt vmcnt(0)
	v_cmp_eq_u32_e32 vcc, v0, v1
	s_and_saveexec_b64 s[12:13], vcc
	s_cbranch_execz .LBB0_644
	s_mov_b32 s7, 1
	s_mov_b64 s[16:17], 0
	s_branch .LBB0_635

.LBB0_644:
	s_or_b64 exec, exec, s[12:13]
	s_waitcnt vmcnt(0)
	s_waitcnt vmcnt(0)
	v_readlane_b32 s87, v254, 62
	v_readlane_b32 s94, v253, 3
